# sample attention: L2 touch of the second unit's cache block during the first unit's wave-0 block (workgroups 192..255)
# baseline (speedup 1.0000x reference)
; #define LAS __attribute__((address_space(3)))
; __device__ __forceinline__ void attn_sample_unit(const Args& a, LAS unsigned char* lds, int l, int b, int kvh, int tid) {
;     ...
;     const float* ck = a.in[I_CK] + ((size_t)l * DEC_B + b) * WIN * 128 + kvh * 64; const float* cv = a.in[I_CV] + ((size_t)l * DEC_B + b) * WIN * 128 + kvh * 64;
;     float* ko = a.out + O_KS + ((size_t)l * DEC_B + b) * WIN * 128 + kvh * 64; float* vo = a.out + O_VS + ((size_t)l * DEC_B + b) * WIN * 128 + kvh * 64;
;     const size_t zrow0 = (size_t)NTOK_P + b * DEC_T;
;     const int lane = tid & 63, r = lane & 15, qd = lane >> 4, t = r >> 2, h = kvh * 4 + (r & 3);
;     u32x4 qraw[2];
;     { const bf16_t* zq = Z + (zrow0 + t) * INC + ZQ + h * 64 + 8 * qd; qraw[0] = *(const u32x4*)zq; qraw[1] = *(const u32x4*)(zq + 32); }
;     {
;         f32x4 kv[4], vv[4];
; #pragma unroll
;     ...
;     if (tid < 64) {
;         const float cs = 0.125f * LOG2E, sinkl = a.in[I_SINK][l * 8 + h] * LOG2E, slope = exp2f(-(float)(h + 1)) * LOG2E;
;         bf16x8 qf[2];
;         {   float x[16]; { float t8[8]; unpack8(qraw[0], t8);
; #pragma unroll
;                 for (int k = 0; k < 8; ++k) x[k] = t8[k];
;                 unpack8(qraw[1], t8);
; #pragma unroll
;                 for (int k = 0; k < 8; ++k) x[8 + k] = t8[k]; }
;             float sq = 0.f;
; #pragma unroll
;             for (int k = 0; k < 16; ++k) sq += x[k] * x[k];
;             sq += __shfl_xor(sq, 16); sq += __shfl_xor(sq, 32);
;             const float rs = rsqrtf(sq * (1.f / 64.f) + EPS) * cs;
; #pragma unroll
;             for (int k = 0; k < 16; ++k) x[k] = x[k] * rs * gq[(k >> 3) * 32 + 8 * qd + (k & 7)];
; #pragma unroll
;             for (int s = 0; s < 2; ++s) { u32x4 w; w.x = pk2(x[8 * s], x[8 * s + 1]); w.y = pk2(x[8 * s + 2], x[8 * s + 3]); w.z = pk2(x[8 * s + 4], x[8 * s + 5]); w.w = pk2(x[8 * s + 6], x[8 * s + 7]);
;                 qf[s] = __builtin_bit_cast(bf16x8, w); } }
;         f32x4 S[NKP / 16]; float mx = -1e30f;
; #pragma unroll
;         for (int T = 0; T < NKP / 16; ++T) {
;             const bf16x8 k0 = *(const LAS bf16x8*)(Ks + (16 * T + r) * KST + 8 * qd), k1 = *(const LAS bf16x8*)(Ks + (16 * T + r) * KST + 32 + 8 * qd);
;             S[T] = __builtin_amdgcn_mfma_f32_16x16x32_bf16(k0, qf[0], (f32x4){0.f, 0.f, 0.f, 0.f}, 0, 0, 0); S[T] = __builtin_amdgcn_mfma_f32_16x16x32_bf16(k1, qf[1], S[T], 0, 0, 0); }
.LBB0_609:
	s_or_b64 exec, exec, s[8:9]
	v_cmp_gt_i32_e32 vcc, 64, v77
	s_waitcnt lgkmcnt(0)
	s_barrier
	s_add_i32 s98, s16, 1
	s_cmp_lt_i32 s98, s13
	s_cbranch_scc0 .Lsp2_skip
	s_mul_i32 s98, s98, s12
	s_add_i32 s98, s98, s14
	s_and_b32 s98, s98, 0xff
	v_readlane_b32 s99, v255, 41
	s_lshr_b32 s100, s98, 1
	s_and_b32 s98, s98, 1
	s_lshl_b32 s99, s99, 7
	s_add_i32 s100, s100, s99
	s_lshl_b32 s98, s98, 8
	s_lshl_b32 s100, s100, 16
	s_add_i32 s98, s100, s98
	v_and_b32_e32 v116, 0xff, v184
	v_lshrrev_b32_e32 v117, 1, v116
	v_and_b32_e32 v116, 1, v116
	v_lshlrev_b32_e32 v117, 9, v117
	v_lshl_add_u32 v116, v116, 7, v117
	v_add_u32_e32 v116, s98, v116
	v_mov_b32_e32 v117, 0
	v_mov_b32_e32 v118, s54
	v_mov_b32_e32 v119, s55
	v_mov_b32_e32 v120, s52
	v_mov_b32_e32 v121, s53
	v_lshrrev_b32_e32 v148, 8, v184
	v_cmp_eq_u32_e64 s[100:101], 0, v148
	s_nop 1
	v_cndmask_b32_e64 v118, v118, v120, s[100:101]
	v_cndmask_b32_e64 v119, v119, v121, s[100:101]
	v_lshl_add_u64 v[118:119], v[118:119], 0, v[116:117]
	global_load_dword v116, v[118:119], off
.Lsp2_skip:
	s_and_saveexec_b64 s[6:7], vcc
	s_cbranch_execz .LBB0_595
	v_lshlrev_b32_e32 v0, 2, v60
	v_mov_b64_e32 v[30:31], v[122:123]
	v_mov_b64_e32 v[32:33], v[124:125]
	v_mov_b64_e32 v[34:35], v[126:127]
	v_mov_b64_e32 v[36:37], v[128:129]
	v_mov_b64_e32 v[38:39], v[130:131]
	v_mov_b64_e32 v[40:41], v[132:133]
	v_mov_b64_e32 v[42:43], v[134:135]
	v_mov_b64_e32 v[44:45], v[136:137]
	v_and_b32_e32 v55, 0xffff0000, v24
	v_lshlrev_b32_e32 v54, 16, v24
	v_mul_f32_e32 v29, v55, v55
	v_lshlrev_b32_e32 v56, 16, v25
	v_fmac_f32_e32 v29, v54, v54
	v_and_b32_e32 v57, 0xffff0000, v25
	v_fmac_f32_e32 v29, v56, v56
	v_lshlrev_b32_e32 v58, 16, v26
	v_fmac_f32_e32 v29, v57, v57
	v_and_b32_e32 v59, 0xffff0000, v26
	v_and_b32_e32 v28, 64, v216
	v_fmac_f32_e32 v29, v58, v58
	v_lshlrev_b32_e32 v62, 16, v27
	v_xor_b32_e32 v0, 16, v216
	v_add_u32_e32 v66, 64, v28
	v_fmac_f32_e32 v29, v59, v59
	v_and_b32_e32 v64, 0xffff0000, v27
	v_and_b32_e32 v24, 0xffff0000, v20
	v_lshlrev_b32_e32 v25, 16, v20
	v_cmp_lt_i32_e32 vcc, v0, v66
	v_fmac_f32_e32 v29, v62, v62
	v_pk_mul_f32 v[46:47], v[24:25], v[24:25]
	v_cndmask_b32_e32 v0, v216, v0, vcc
	v_fmac_f32_e32 v29, v64, v64
	v_and_b32_e32 v20, 0xffff0000, v21
	v_lshlrev_b32_e32 v21, 16, v21
	v_lshlrev_b32_e32 v28, 2, v0
	v_add_f32_e32 v0, v47, v29
	v_pk_mul_f32 v[48:49], v[20:21], v[20:21]
	v_add_f32_e32 v0, v46, v0
	v_and_b32_e32 v26, 0xffff0000, v22
	v_lshlrev_b32_e32 v27, 16, v22
	v_add_f32_e32 v0, v49, v0
	v_pk_mul_f32 v[50:51], v[26:27], v[26:27]
	v_add_f32_e32 v0, v48, v0
	v_and_b32_e32 v22, 0xffff0000, v23
	v_lshlrev_b32_e32 v23, 16, v23
	v_add_f32_e32 v0, v51, v0
	v_pk_mul_f32 v[52:53], v[22:23], v[22:23]
	v_add_f32_e32 v0, v50, v0
	v_add_f32_e32 v0, v53, v0
	v_add_f32_e32 v0, v52, v0
	ds_bpermute_b32 v46, v28, v0
	v_xor_b32_e32 v29, 32, v216
	v_cmp_lt_i32_e32 vcc, v29, v66
	v_readlane_b32 s52, v252, 38
	v_readlane_b32 s58, v252, 44
	v_cndmask_b32_e32 v29, v216, v29, vcc
	v_lshlrev_b32_e32 v29, 2, v29
	s_waitcnt lgkmcnt(0)
	v_add_f32_e32 v0, v0, v46
	ds_bpermute_b32 v46, v29, v0
	v_readlane_b32 s59, v252, 45
	s_mov_b32 s0, 0x42fc0000
	v_lshlrev_b64 v[2:3], 10, v[2:3]
	v_lshl_add_u64 v[2:3], s[36:37], 0, v[2:3]
	s_waitcnt lgkmcnt(0)
	v_add_f32_e32 v0, v0, v46
	v_fmamk_f32 v0, v0, 0x3c800000, v185
	v_mul_f32_e32 v46, 0x4b800000, v0
	v_cmp_gt_f32_e32 vcc, s86, v0
	v_readlane_b32 s53, v252, 39
	v_readlane_b32 s54, v252, 40
	v_cndmask_b32_e32 v0, v0, v46, vcc
	v_rsq_f32_e32 v48, v0
	v_or_b32_e32 v0, s93, v76
	v_lshl_add_u64 v[46:47], v[0:1], 2, s[58:59]
	v_mov_b32_e32 v0, v138
	v_mul_f32_e32 v46, 0x45800000, v48
	v_cndmask_b32_e32 v46, v48, v46, vcc
	v_mul_f32_e32 v46, 0x3e38aa3b, v46
	v_mul_f32_e32 v24, v46, v24
	v_mul_f32_e32 v20, v46, v20
	v_mul_f32_e32 v47, v46, v54
	v_mul_f32_e32 v48, v46, v55
	v_mul_f32_e32 v49, v46, v56
	v_mul_f32_e32 v50, v46, v57
	v_mul_f32_e32 v51, v46, v58
	v_mul_f32_e32 v52, v46, v59
	v_mul_f32_e32 v30, v30, v47
	v_mul_f32_e32 v31, v31, v48
	v_mul_f32_e32 v24, v43, v24
	v_mul_f32_e32 v43, v20, v45
	v_mul_f32_e32 v20, v46, v27
	v_mul_f32_e32 v27, v20, v38
	v_mul_f32_e32 v20, v46, v26
	v_mul_f32_e32 v26, v20, v39
	v_mul_f32_e32 v20, v46, v23
	v_mul_f32_e32 v38, v20, v40
	v_mul_f32_e32 v20, v46, v22
	v_mul_f32_e32 v53, v46, v62
	v_mul_f32_e32 v54, v46, v64
	v_mul_f32_e32 v25, v46, v25
	v_mul_f32_e32 v39, v20, v41
	v_cvt_pk_bf16_f32 v20, v30, v31
	v_mul_u32_u24_e32 v30, 0x90, v63
	v_lshlrev_b32_e32 v31, 1, v60
	v_mul_f32_e32 v32, v32, v49
	v_mul_f32_e32 v33, v33, v50
	v_mul_f32_e32 v34, v34, v51
	v_mul_f32_e32 v35, v35, v52
	v_mul_f32_e32 v36, v36, v53
	v_mul_f32_e32 v37, v37, v54
	v_mul_f32_e32 v25, v42, v25
	v_mul_f32_e32 v21, v46, v21
	v_add3_u32 v58, 0, v30, v31
	v_mul_f32_e32 v42, v21, v44
	v_cvt_pk_bf16_f32 v21, v32, v33
	v_cvt_pk_bf16_f32 v22, v34, v35
	v_cvt_pk_bf16_f32 v23, v36, v37
	v_cvt_pk_bf16_f32 v24, v25, v24
	v_cvt_pk_bf16_f32 v25, v42, v43
	v_cvt_pk_bf16_f32 v26, v27, v26
	v_cvt_pk_bf16_f32 v27, v38, v39
	ds_read_b128 v[30:33], v58
	ds_read_b128 v[34:37], v58 offset:64
	s_waitcnt lgkmcnt(1)
	v_mfma_f32_16x16x32_bf16 v[30:33], v[30:33], v[20:23], 0
	ds_read_b128 v[38:41], v58 offset:2304
	ds_read_b128 v[42:45], v58 offset:4608
	ds_read_b128 v[46:49], v58 offset:6912
	s_waitcnt lgkmcnt(3)
	v_mfma_f32_16x16x32_bf16 v[30:33], v[34:37], v[24:27], v[30:33]
	ds_read_b128 v[34:37], v58 offset:2368
	ds_read_b128 v[50:53], v58 offset:9216
	ds_read_b128 v[54:57], v58 offset:11520
	s_waitcnt lgkmcnt(5)
	v_mfma_f32_16x16x32_bf16 v[38:41], v[38:41], v[20:23], 0
	ds_read_b128 v[66:69], v58 offset:13824
	ds_read_b128 v[70:73], v58 offset:16128
	ds_read_b128 v[78:81], v58 offset:18432
	s_waitcnt lgkmcnt(5)
; #define LAS __attribute__((address_space(3)))
; __device__ __forceinline__ void attn_sample_unit(const Args& a, LAS unsigned char* lds, int l, int b, int kvh, int tid) {
;     ...
;         f32x4 S[NKP / 16]; float mx = -1e30f;
; #pragma unroll
;         for (int T = 0; T < NKP / 16; ++T) {
;             const bf16x8 k0 = *(const LAS bf16x8*)(Ks + (16 * T + r) * KST + 8 * qd), k1 = *(const LAS bf16x8*)(Ks + (16 * T + r) * KST + 32 + 8 * qd);
;             S[T] = __builtin_amdgcn_mfma_f32_16x16x32_bf16(k0, qf[0], (f32x4){0.f, 0.f, 0.f, 0.f}, 0, 0, 0); S[T] = __builtin_amdgcn_mfma_f32_16x16x32_bf16(k1, qf[1], S[T], 0, 0, 0); }
; #pragma unroll
;         for (int T = 0; T < NKP / 16; ++T)
; #pragma unroll
;             for (int i = 0; i < 4; ++i) { const int dist = WIN + t - (16 * T + 4 * qd + i);
;                 const float s = (unsigned)dist <= (unsigned)WIN ? S[T][i] - slope * (float)dist : -1e30f; S[T][i] = s; mx = fmaxf(mx, s); }
;         mx = fmaxf(mx, __shfl_xor(mx, 16)); mx = fmaxf(mx, __shfl_xor(mx, 32)); mx = fmaxf(mx, sinkl);
	v_mfma_f32_16x16x32_bf16 v[34:37], v[34:37], v[24:27], v[38:41]
	v_add_u32_e32 v59, 1, v76
	v_cvt_f32_ubyte0_e32 v59, v59
	v_cmp_lt_f32_e32 vcc, s0, v59
	ds_read_b128 v[38:41], v58 offset:4672
	v_mfma_f32_16x16x32_bf16 v[42:45], v[42:45], v[20:23], 0
	v_lshlrev_b32_e32 v62, 2, v65
	s_mov_b32 s0, 0xf149f2ca
	v_readlane_b32 s55, v252, 41
	s_waitcnt lgkmcnt(0)
	v_mfma_f32_16x16x32_bf16 v[38:41], v[38:41], v[24:27], v[42:45]
	s_nop 2
	ds_read_b128 v[42:45], v58 offset:6976
	v_readlane_b32 s56, v252, 42
	v_readlane_b32 s57, v252, 43
	v_mfma_f32_16x16x32_bf16 v[46:49], v[46:49], v[20:23], 0
	v_readlane_b32 s60, v252, 46
	v_readlane_b32 s61, v252, 47
	v_readlane_b32 s62, v252, 48
	s_waitcnt lgkmcnt(0)
	v_mfma_f32_16x16x32_bf16 v[42:45], v[42:45], v[24:27], v[46:49]
	v_readlane_b32 s63, v252, 49
	s_nop 1
	ds_read_b128 v[46:49], v58 offset:9280
	v_readlane_b32 s64, v252, 50
	v_mfma_f32_16x16x32_bf16 v[50:53], v[50:53], v[20:23], 0
	v_readlane_b32 s65, v252, 51
	v_readlane_b32 s66, v252, 52
	v_readlane_b32 s67, v252, 53
	s_waitcnt lgkmcnt(0)
	v_mfma_f32_16x16x32_bf16 v[46:49], v[46:49], v[24:27], v[50:53]
	v_readlane_b32 s52, v252, 0
	s_nop 1
	ds_read_b128 v[50:53], v58 offset:11584
	v_readlane_b32 s53, v252, 1
	v_mfma_f32_16x16x32_bf16 v[54:57], v[54:57], v[20:23], 0
	v_readlane_b32 s54, v252, 2
	v_readlane_b32 s55, v252, 3
	v_readlane_b32 s56, v252, 4
	s_waitcnt lgkmcnt(0)
	v_mfma_f32_16x16x32_bf16 v[50:53], v[50:53], v[24:27], v[54:57]
	v_readlane_b32 s57, v252, 5
	s_nop 1
	ds_read_b128 v[54:57], v58 offset:13888
	v_readlane_b32 s58, v252, 6
	v_mfma_f32_16x16x32_bf16 v[66:69], v[66:69], v[20:23], 0
	v_readlane_b32 s59, v252, 7
	v_readlane_b32 s60, v252, 8
	v_readlane_b32 s61, v252, 9
	s_waitcnt lgkmcnt(0)
	v_mfma_f32_16x16x32_bf16 v[54:57], v[54:57], v[24:27], v[66:69]
	v_readlane_b32 s62, v252, 10
	s_nop 1
	ds_read_b128 v[66:69], v58 offset:16192
	v_readlane_b32 s63, v252, 11
	v_mfma_f32_16x16x32_bf16 v[70:73], v[70:73], v[20:23], 0
	s_mov_b64 s[52:53], s[56:57]
	s_mov_b64 s[54:55], s[58:59]
	v_readlane_b32 s64, v252, 12
	s_waitcnt lgkmcnt(0)
	v_mfma_f32_16x16x32_bf16 v[66:69], v[66:69], v[24:27], v[70:73]
	v_readlane_b32 s65, v252, 13
	s_nop 1
	ds_read_b128 v[70:73], v58 offset:18496
	v_mov_b32_e32 v58, 0x42800000
	v_cndmask_b32_e32 v58, 0, v58, vcc
	v_sub_f32_e32 v58, v58, v59
	v_exp_f32_e32 v58, v58
	v_mfma_f32_16x16x32_bf16 v[20:23], v[78:81], v[20:23], 0
	v_not_b32_e32 v59, 63
	v_cndmask_b32_e32 v59, 0, v59, vcc
	v_ldexp_f32 v58, v58, v59
	v_or_b32_e32 v59, 0x80, v75
	v_sub_u32_e32 v64, v59, v62
	s_waitcnt lgkmcnt(0)
	v_mfma_f32_16x16x32_bf16 v[70:73], v[70:73], v[24:27], v[20:23]
	v_mul_f32_e32 v58, 0x3fb8aa3b, v58
	v_cmp_gt_u32_e32 vcc, s81, v64
	v_mov_b32_e32 v79, 0xf149f2ca
	v_cvt_f32_ubyte0_e32 v20, v64
	v_fma_f32 v20, -v58, v20, v30
	v_cndmask_b32_e32 v65, v79, v20, vcc
	v_xad_u32 v20, v62, -1, v59
	v_cvt_f32_ubyte0_e32 v21, v20
	v_cmp_gt_u32_e32 vcc, s81, v20
	v_or_b32_e32 v20, 2, v62
	v_fma_f32 v21, -v58, v21, v31
	v_sub_u32_e32 v20, v59, v20
	v_cndmask_b32_e32 v74, v79, v21, vcc
	v_cvt_f32_ubyte0_e32 v21, v20
	v_fma_f32 v21, -v58, v21, v32
	v_cmp_gt_u32_e32 vcc, s81, v20
	v_add_u32_e32 v20, -3, v64
	v_cvt_f32_u32_e32 v23, v20
	v_cndmask_b32_e32 v76, v79, v21, vcc
	v_add_u32_e32 v20, -16, v64
	v_subrev_u32_e32 v21, 17, v64
	v_cvt_f32_u32_e32 v21, v21
	v_cvt_f32_u32_e32 v20, v20
	v_max_f32_e32 v22, 0xf149f2ca, v65
	v_max3_f32 v24, v22, v74, v76
	v_fma_f32 v77, -v58, v23, v33
	v_pk_fma_f32 v[30:31], v[58:59], v[20:21], v[34:35] op_sel_hi:[0,1,1] neg_lo:[1,0,0] neg_hi:[1,0,0]
	v_subrev_u32_e32 v20, 18, v64
	v_subrev_u32_e32 v21, 19, v64
	v_cvt_f32_u32_e32 v21, v21
	v_cvt_f32_u32_e32 v20, v20
	v_subrev_u32_e32 v22, 32, v64
	v_subrev_u32_e32 v23, 33, v64
	v_cvt_f32_u32_e32 v23, v23
	v_cvt_f32_u32_e32 v22, v22
	v_pk_fma_f32 v[32:33], v[58:59], v[20:21], v[36:37] op_sel_hi:[0,1,1] neg_lo:[1,0,0] neg_hi:[1,0,0]
	v_subrev_u32_e32 v20, 34, v64
	v_subrev_u32_e32 v21, 35, v64
	v_cvt_f32_u32_e32 v21, v21
	v_cvt_f32_u32_e32 v20, v20
	v_pk_fma_f32 v[34:35], v[58:59], v[22:23], v[38:39] op_sel_hi:[0,1,1] neg_lo:[1,0,0] neg_hi:[1,0,0]
	v_subrev_u32_e32 v22, 48, v64
	v_subrev_u32_e32 v23, 49, v64
	v_cvt_f32_u32_e32 v23, v23
	v_cvt_f32_u32_e32 v22, v22
	v_pk_fma_f32 v[36:37], v[58:59], v[20:21], v[40:41] op_sel_hi:[0,1,1] neg_lo:[1,0,0] neg_hi:[1,0,0]
	v_subrev_u32_e32 v20, 50, v64
	v_subrev_u32_e32 v21, 51, v64
	v_cvt_f32_u32_e32 v21, v21
	v_cvt_f32_u32_e32 v20, v20
	v_pk_fma_f32 v[38:39], v[58:59], v[22:23], v[42:43] op_sel_hi:[0,1,1] neg_lo:[1,0,0] neg_hi:[1,0,0]
	v_subrev_u32_e32 v22, 64, v64
	v_add_u32_e32 v23, 0xffffffbf, v64
	v_cvt_f32_u32_e32 v23, v23
	v_cvt_f32_u32_e32 v22, v22
	v_pk_fma_f32 v[40:41], v[58:59], v[20:21], v[44:45] op_sel_hi:[0,1,1] neg_lo:[1,0,0] neg_hi:[1,0,0]
	v_add_u32_e32 v20, 0xffffffbe, v64
	v_add_u32_e32 v21, 0xffffffbd, v64
	v_cvt_f32_u32_e32 v21, v21
	v_cvt_f32_u32_e32 v20, v20
	v_pk_fma_f32 v[42:43], v[58:59], v[22:23], v[46:47] op_sel_hi:[0,1,1] neg_lo:[1,0,0] neg_hi:[1,0,0]
	v_add_u32_e32 v22, 0xffffffb0, v64
	v_add_u32_e32 v23, 0xffffffaf, v64
	v_max3_f32 v24, v24, v77, v30
	v_cvt_f32_u32_e32 v23, v23
	v_cvt_f32_u32_e32 v22, v22
	v_pk_fma_f32 v[44:45], v[58:59], v[20:21], v[48:49] op_sel_hi:[0,1,1] neg_lo:[1,0,0] neg_hi:[1,0,0]
	v_add_u32_e32 v20, 0xffffffae, v64
	v_add_u32_e32 v21, 0xffffffad, v64
	v_max3_f32 v24, v24, v31, v32
	v_cvt_f32_u32_e32 v21, v21
	v_cvt_f32_u32_e32 v20, v20
	v_max3_f32 v24, v24, v33, v34
	v_max3_f32 v24, v24, v35, v36
	v_max3_f32 v24, v24, v37, v38
	v_pk_fma_f32 v[46:47], v[58:59], v[22:23], v[50:51] op_sel_hi:[0,1,1] neg_lo:[1,0,0] neg_hi:[1,0,0]
	v_add_u32_e32 v22, 0xffffffa0, v64
; __device__ __forceinline__ void attn_sample_unit(const Args& a, LAS unsigned char* lds, int l, int b, int kvh, int tid) {
;     ...
; #pragma unroll
;         for (int T = 0; T < NKP / 16; ++T)
; #pragma unroll
;             for (int i = 0; i < 4; ++i) { const int dist = WIN + t - (16 * T + 4 * qd + i);
;                 const float s = (unsigned)dist <= (unsigned)WIN ? S[T][i] - slope * (float)dist : -1e30f; S[T][i] = s; mx = fmaxf(mx, s); }
;         mx = fmaxf(mx, __shfl_xor(mx, 16)); mx = fmaxf(mx, __shfl_xor(mx, 32)); mx = fmaxf(mx, sinkl);
;         float lsum = 0.f;
; #pragma unroll
;         for (int T = 0; T < NKP / 16; ++T)
; #pragma unroll
;             for (int i = 0; i < 4; ++i) { const float p = S[T][i] > -1e29f ? __builtin_amdgcn_exp2f(S[T][i] - mx) : 0.f; S[T][i] = p; lsum += p; }
	v_add_u32_e32 v23, 0xffffff9f, v64
	v_max3_f32 v24, v24, v39, v40
	v_cvt_f32_u32_e32 v23, v23
	v_cvt_f32_u32_e32 v22, v22
	v_pk_fma_f32 v[48:49], v[58:59], v[20:21], v[52:53] op_sel_hi:[0,1,1] neg_lo:[1,0,0] neg_hi:[1,0,0]
	v_add_u32_e32 v20, 0xffffff9e, v64
	v_add_u32_e32 v21, 0xffffff9d, v64
	v_max3_f32 v24, v24, v41, v42
	v_cvt_f32_u32_e32 v21, v21
	v_cvt_f32_u32_e32 v20, v20
	v_max3_f32 v24, v24, v43, v44
	v_max3_f32 v24, v24, v45, v46
	v_or_b32_e32 v78, 0x81, v62
	v_max3_f32 v24, v24, v47, v48
	v_pk_fma_f32 v[26:27], v[58:59], v[22:23], v[54:55] op_sel_hi:[0,1,1] neg_lo:[1,0,0] neg_hi:[1,0,0]
	v_add_u32_e32 v22, 0xffffff90, v64
	v_add_u32_e32 v23, 0xffffff8f, v64
	v_cvt_f32_u32_e32 v23, v23
	v_cvt_f32_u32_e32 v22, v22
	v_max3_f32 v50, v24, v49, v26
	v_pk_fma_f32 v[24:25], v[58:59], v[20:21], v[56:57] op_sel_hi:[0,1,1] neg_lo:[1,0,0] neg_hi:[1,0,0]
	v_add_u32_e32 v20, 0xffffff8e, v64
	v_add_u32_e32 v21, 0xffffff8d, v64
	v_sub_u32_e32 v53, v59, v78
	v_sub_u32_e32 v54, v75, v62
	v_max3_f32 v52, v50, v27, v24
	v_cvt_f32_u32_e32 v21, v21
	v_cvt_f32_u32_e32 v20, v20
	v_cvt_f32_u32_e32 v51, v53
	v_cvt_f32_u32_e32 v50, v54
	v_pk_fma_f32 v[22:23], v[58:59], v[22:23], v[66:67] op_sel_hi:[0,1,1] neg_lo:[1,0,0] neg_hi:[1,0,0]
	v_max3_f32 v52, v52, v25, v22
	v_pk_fma_f32 v[20:21], v[58:59], v[20:21], v[68:69] op_sel_hi:[0,1,1] neg_lo:[1,0,0] neg_hi:[1,0,0]
	v_pk_fma_f32 v[50:51], v[58:59], v[50:51], v[70:71] op_sel_hi:[0,1,1] neg_lo:[1,0,0] neg_hi:[1,0,0]
	v_cmp_gt_u32_e32 vcc, s81, v53
	v_max3_f32 v55, v52, v23, v20
	v_or_b32_e32 v52, 0x82, v62
	v_cndmask_b32_e32 v64, v79, v51, vcc
	v_or_b32_e32 v51, 0x83, v62
	v_sub_u32_e32 v56, v59, v51
	v_sub_u32_e32 v57, v59, v52
	v_cvt_f32_u32_e32 v53, v56
	v_cvt_f32_u32_e32 v52, v57
	v_cmp_gt_u32_e32 vcc, s81, v54
	v_readlane_b32 s66, v252, 14
	v_readlane_b32 s67, v252, 15
	v_cndmask_b32_e32 v59, v79, v50, vcc
	v_pk_fma_f32 v[50:51], v[58:59], v[52:53], v[72:73] op_sel_hi:[0,1,1] neg_lo:[1,0,0] neg_hi:[1,0,0]
	v_cmp_gt_u32_e32 vcc, s81, v56
	v_max3_f32 v54, v55, v21, v59
	v_mul_f32_e32 v52, 0x3fb8aa3b, v0
	v_cndmask_b32_e32 v58, v79, v51, vcc
	v_cmp_gt_u32_e32 vcc, s81, v57
	s_mov_b64 s[56:57], s[60:61]
	s_mov_b64 s[58:59], s[62:63]
	v_cndmask_b32_e32 v62, v79, v50, vcc
	v_max3_f32 v50, v54, v64, v62
	v_max3_f32 v50, v50, v58, s0
	ds_bpermute_b32 v51, v28, v50
	v_cmp_lt_f32_e32 vcc, s92, v65
	s_mov_b32 s0, 0x3fb8aa3b
	s_waitcnt lgkmcnt(0)
	v_max_f32_e32 v51, v51, v51
	v_max_f32_e32 v50, v50, v51
	ds_bpermute_b32 v51, v29, v50
	s_waitcnt lgkmcnt(0)
	v_max3_f32 v66, v50, v51, v52
	v_sub_f32_e32 v50, v65, v66
	v_exp_f32_e32 v50, v50
	v_sub_f32_e32 v52, v74, v66
	v_exp_f32_e32 v52, v52
	v_sub_f32_e32 v53, v76, v66
	v_exp_f32_e32 v53, v53
	v_sub_f32_e32 v54, v77, v66
	v_exp_f32_e32 v54, v54
	v_sub_f32_e32 v55, v30, v66
	v_cndmask_b32_e32 v50, 0, v50, vcc
	v_cmp_lt_f32_e32 vcc, s92, v74
	v_exp_f32_e32 v55, v55
	v_add_f32_e32 v51, 0, v50
	v_cndmask_b32_e32 v52, 0, v52, vcc
	v_cmp_lt_f32_e32 vcc, s92, v76
	v_add_f32_e32 v51, v52, v51
	v_sub_f32_e32 v56, v32, v66
	v_cndmask_b32_e32 v53, 0, v53, vcc
	v_cmp_lt_f32_e32 vcc, s92, v77
	v_add_f32_e32 v51, v53, v51
	v_exp_f32_e32 v56, v56
	v_cndmask_b32_e32 v54, 0, v54, vcc
	v_cmp_lt_f32_e32 vcc, s92, v30
	v_add_f32_e32 v51, v54, v51
	v_fma_f32 v0, v0, s0, -v66
	v_cndmask_b32_e32 v55, 0, v55, vcc
	v_add_f32_e32 v30, v55, v51
	v_sub_f32_e32 v51, v31, v66
	v_exp_f32_e32 v51, v51
	v_cmp_lt_f32_e32 vcc, s92, v31
	v_sub_f32_e32 v31, v33, v66
	v_exp_f32_e32 v31, v31
	v_cndmask_b32_e32 v51, 0, v51, vcc
	v_cmp_lt_f32_e32 vcc, s92, v32
	v_sub_f32_e32 v32, v34, v66
	v_exp_f32_e32 v32, v32
	v_cndmask_b32_e32 v56, 0, v56, vcc
	v_cmp_lt_f32_e32 vcc, s92, v33
	v_add_f32_e32 v30, v51, v30
	v_add_f32_e32 v30, v56, v30
	v_cndmask_b32_e32 v33, 0, v31, vcc
	v_cmp_lt_f32_e32 vcc, s92, v34
	v_sub_f32_e32 v31, v35, v66
	v_exp_f32_e32 v31, v31
	v_cndmask_b32_e32 v57, 0, v32, vcc
	v_sub_f32_e32 v32, v36, v66
	v_exp_f32_e32 v32, v32
	v_cmp_lt_f32_e32 vcc, s92, v35
	v_add_f32_e32 v30, v33, v30
	v_add_f32_e32 v30, v57, v30
	v_cndmask_b32_e32 v65, 0, v31, vcc
	v_cmp_lt_f32_e32 vcc, s92, v36
	v_sub_f32_e32 v31, v37, v66
	v_exp_f32_e32 v31, v31
	v_cndmask_b32_e32 v67, 0, v32, vcc
	v_sub_f32_e32 v32, v38, v66
	v_exp_f32_e32 v32, v32
	v_cmp_lt_f32_e32 vcc, s92, v37
	v_add_f32_e32 v30, v65, v30
	v_add_f32_e32 v30, v67, v30
	v_cndmask_b32_e32 v68, 0, v31, vcc
	v_cmp_lt_f32_e32 vcc, s92, v38
	v_sub_f32_e32 v31, v39, v66
	v_exp_f32_e32 v31, v31
	v_cndmask_b32_e32 v69, 0, v32, vcc
	v_sub_f32_e32 v32, v40, v66
	v_exp_f32_e32 v32, v32
	v_cmp_lt_f32_e32 vcc, s92, v39
	v_add_f32_e32 v30, v68, v30
	v_add_f32_e32 v30, v69, v30
	v_cndmask_b32_e32 v70, 0, v31, vcc
	v_cmp_lt_f32_e32 vcc, s92, v40
	v_sub_f32_e32 v31, v41, v66
	v_exp_f32_e32 v31, v31
	v_cndmask_b32_e32 v71, 0, v32, vcc
	v_sub_f32_e32 v32, v42, v66
	v_exp_f32_e32 v32, v32
	v_cmp_lt_f32_e32 vcc, s92, v41
	v_add_f32_e32 v30, v70, v30
	v_add_f32_e32 v30, v71, v30
	v_cndmask_b32_e32 v72, 0, v31, vcc
	v_cmp_lt_f32_e32 vcc, s92, v42
	v_sub_f32_e32 v31, v43, v66
	v_exp_f32_e32 v31, v31
	v_cndmask_b32_e32 v73, 0, v32, vcc
	v_sub_f32_e32 v32, v44, v66
	v_exp_f32_e32 v32, v32
	v_cmp_lt_f32_e32 vcc, s92, v43
	v_add_f32_e32 v30, v72, v30
	v_add_f32_e32 v30, v73, v30
	v_cndmask_b32_e32 v74, 0, v31, vcc
	v_cmp_lt_f32_e32 vcc, s92, v44
	v_sub_f32_e32 v31, v45, v66
	v_exp_f32_e32 v31, v31
	v_cndmask_b32_e32 v75, 0, v32, vcc
	v_sub_f32_e32 v32, v46, v66
	v_exp_f32_e32 v32, v32
	v_cmp_lt_f32_e32 vcc, s92, v45
	v_add_f32_e32 v30, v74, v30
	v_add_f32_e32 v30, v75, v30
	v_cndmask_b32_e32 v76, 0, v31, vcc
	v_cmp_lt_f32_e32 vcc, s92, v46
	v_sub_f32_e32 v31, v47, v66
; #define LAS __attribute__((address_space(3)))
; __device__ __forceinline__ unsigned pk2(float lo, float hi) { return pg8::cvt_pk_bf16(lo, hi); }
; __device__ __forceinline__ void attn_sample_unit(const Args& a, LAS unsigned char* lds, int l, int b, int kvh, int tid) {
;     ...
;         for (int T = 0; T < NKP / 16; ++T)
; #pragma unroll
;             for (int i = 0; i < 4; ++i) { const float p = S[T][i] > -1e29f ? __builtin_amdgcn_exp2f(S[T][i] - mx) : 0.f; S[T][i] = p; lsum += p; }
;         f32x4 O[4];
; #pragma unroll
;         for (int dt = 0; dt < 4; ++dt) O[dt] = (f32x4){0.f, 0.f, 0.f, 0.f};
; #pragma unroll
;         for (int st = 0; st < NKP / 32; ++st) {
;             u32x4 w; w.x = pk2(S[2 * st][0], S[2 * st][1]); w.y = pk2(S[2 * st][2], S[2 * st][3]); w.z = pk2(S[2 * st + 1][0], S[2 * st + 1][1]); w.w = pk2(S[2 * st + 1][2], S[2 * st + 1][3]);
;             const bf16x8 pf = __builtin_bit_cast(bf16x8, w);
; #pragma unroll
;             for (int dt = 0; dt < 4; ++dt) { const u32x2 lo = *(const LAS u32x2*)(Vt + (dt * 16 + r) * VST + 32 * st + 4 * qd), hi = *(const LAS u32x2*)(Vt + (dt * 16 + r) * VST + 32 * st + 16 + 4 * qd);
;                 O[dt] = __builtin_amdgcn_mfma_f32_16x16x32_bf16(__builtin_bit_cast(bf16x8, (u32x4){lo.x, lo.y, hi.x, hi.y}), pf, O[dt], 0, 0, 0); }
	v_exp_f32_e32 v31, v31
	v_cndmask_b32_e32 v77, 0, v32, vcc
	v_sub_f32_e32 v32, v48, v66
	v_exp_f32_e32 v32, v32
	v_cmp_lt_f32_e32 vcc, s92, v47
	v_add_f32_e32 v30, v76, v30
	v_add_f32_e32 v30, v77, v30
	v_cndmask_b32_e32 v78, 0, v31, vcc
	v_cmp_lt_f32_e32 vcc, s92, v48
	v_sub_f32_e32 v31, v49, v66
	v_exp_f32_e32 v31, v31
	v_cndmask_b32_e32 v79, 0, v32, vcc
	v_sub_f32_e32 v32, v26, v66
	v_exp_f32_e32 v32, v32
	v_add_f32_e32 v30, v78, v30
	v_cmp_lt_f32_e32 vcc, s92, v49
	v_mul_u32_u24_e32 v34, 0x160, v63
	v_add_f32_e32 v30, v79, v30
	v_cndmask_b32_e32 v80, 0, v31, vcc
	v_cmp_lt_f32_e32 vcc, s92, v26
	v_add3_u32 v46, 0, v34, v60
	v_sub_f32_e32 v38, v27, v66
	v_add_f32_e32 v30, v80, v30
	v_cndmask_b32_e32 v81, 0, v32, vcc
	v_add_u32_e32 v63, 0x5800, v46
	v_exp_f32_e32 v42, v38
	v_add_f32_e32 v26, v81, v30
	v_cvt_pk_bf16_f32 v30, v50, v52
	v_cvt_pk_bf16_f32 v31, v53, v54
	v_cvt_pk_bf16_f32 v32, v55, v51
	v_cvt_pk_bf16_f32 v33, v56, v33
	ds_read2_b64 v[34:37], v63 offset0:64 offset1:68
	v_add_u32_e32 v82, 0x7000, v46
	v_cmp_lt_f32_e32 vcc, s92, v27
	v_add_u32_e32 v84, 0x8000, v46
	v_add_u32_e32 v85, 0x9800, v46
	ds_read2_b64 v[38:41], v82 offset1:4
	v_cndmask_b32_e32 v83, 0, v42, vcc
	ds_read2_b64 v[42:45], v84 offset0:192 offset1:196
	ds_read2_b64 v[46:49], v85 offset0:128 offset1:132
	v_cvt_pk_bf16_f32 v50, v57, v65
	v_cvt_pk_bf16_f32 v51, v67, v68
	v_cvt_pk_bf16_f32 v52, v69, v70
	v_cvt_pk_bf16_f32 v53, v71, v72
	ds_read2_b64 v[54:57], v63 offset0:72 offset1:76
	v_sub_f32_e32 v27, v24, v66
	s_waitcnt lgkmcnt(4)
	v_mfma_f32_16x16x32_bf16 v[34:37], v[34:37], v[30:33], 0
	v_exp_f32_e32 v27, v27
	v_cmp_lt_f32_e32 vcc, s92, v24
	v_add_f32_e32 v26, v83, v26
	s_waitcnt lgkmcnt(3)
	v_mfma_f32_16x16x32_bf16 v[38:41], v[38:41], v[30:33], 0
	v_cndmask_b32_e32 v65, 0, v27, vcc
	v_add_f32_e32 v24, v65, v26
	v_sub_f32_e32 v26, v25, v66
	s_waitcnt lgkmcnt(2)
	v_mfma_f32_16x16x32_bf16 v[42:45], v[42:45], v[30:33], 0
	v_exp_f32_e32 v26, v26
	v_cmp_lt_f32_e32 vcc, s92, v25
	v_sub_f32_e32 v69, v22, v66
	s_waitcnt lgkmcnt(1)
	v_mfma_f32_16x16x32_bf16 v[30:33], v[46:49], v[30:33], 0
	ds_read2_b64 v[46:49], v82 offset0:8 offset1:12
	v_cndmask_b32_e32 v67, 0, v26, vcc
	v_add_f32_e32 v68, v67, v24
	s_waitcnt lgkmcnt(1)
	v_mfma_f32_16x16x32_bf16 v[34:37], v[54:57], v[50:53], v[34:37]
	ds_read2_b64 v[54:57], v84 offset0:200 offset1:204
	v_exp_f32_e32 v69, v69
	v_cmp_lt_f32_e32 vcc, s92, v22
	s_waitcnt lgkmcnt(1)
	v_mfma_f32_16x16x32_bf16 v[24:27], v[46:49], v[50:53], v[38:41]
	v_sub_f32_e32 v22, v20, v66
	s_nop 1
	v_sub_f32_e32 v38, v23, v66
	v_exp_f32_e32 v70, v38
	s_waitcnt lgkmcnt(0)
	v_mfma_f32_16x16x32_bf16 v[38:41], v[54:57], v[50:53], v[42:45]
	v_exp_f32_e32 v22, v22
	v_cndmask_b32_e32 v69, 0, v69, vcc
	v_cmp_lt_f32_e32 vcc, s92, v23
	ds_read2_b64 v[42:45], v85 offset0:136 offset1:140
	v_cvt_pk_bf16_f32 v46, v73, v74
	v_cvt_pk_bf16_f32 v47, v75, v76
	v_cvt_pk_bf16_f32 v48, v77, v78
	v_cvt_pk_bf16_f32 v49, v79, v80
	ds_read2_b64 v[54:57], v63 offset0:80 offset1:84
	s_waitcnt lgkmcnt(1)
	v_mfma_f32_16x16x32_bf16 v[30:33], v[42:45], v[50:53], v[30:33]
	ds_read2_b64 v[42:45], v82 offset0:16 offset1:20
	v_cndmask_b32_e32 v70, 0, v70, vcc
	v_sub_f32_e32 v23, v21, v66
	ds_read2_b64 v[50:53], v84 offset0:208 offset1:212
	v_cmp_lt_f32_e32 vcc, s92, v20
	s_waitcnt lgkmcnt(2)
	v_mfma_f32_16x16x32_bf16 v[34:37], v[54:57], v[46:49], v[34:37]
	v_exp_f32_e32 v54, v23
	v_cndmask_b32_e32 v71, 0, v22, vcc
	v_sub_f32_e32 v20, v59, v66
	s_waitcnt lgkmcnt(1)
	v_mfma_f32_16x16x32_bf16 v[22:25], v[42:45], v[46:49], v[24:27]
	ds_read2_b64 v[42:45], v85 offset0:144 offset1:148
	v_exp_f32_e32 v20, v20
	v_cmp_lt_f32_e32 vcc, s92, v21
	s_waitcnt lgkmcnt(1)
; #define LAS __attribute__((address_space(3)))
; __device__ __forceinline__ unsigned pk2(float lo, float hi) { return pg8::cvt_pk_bf16(lo, hi); }
; __device__ __forceinline__ void attn_sample_unit(const Args& a, LAS unsigned char* lds, int l, int b, int kvh, int tid) {
;     ...
;         for (int st = 0; st < NKP / 32; ++st) {
;             u32x4 w; w.x = pk2(S[2 * st][0], S[2 * st][1]); w.y = pk2(S[2 * st][2], S[2 * st][3]); w.z = pk2(S[2 * st + 1][0], S[2 * st + 1][1]); w.w = pk2(S[2 * st + 1][2], S[2 * st + 1][3]);
;             const bf16x8 pf = __builtin_bit_cast(bf16x8, w);
; #pragma unroll
;             for (int dt = 0; dt < 4; ++dt) { const u32x2 lo = *(const LAS u32x2*)(Vt + (dt * 16 + r) * VST + 32 * st + 4 * qd), hi = *(const LAS u32x2*)(Vt + (dt * 16 + r) * VST + 32 * st + 16 + 4 * qd);
;                 O[dt] = __builtin_amdgcn_mfma_f32_16x16x32_bf16(__builtin_bit_cast(bf16x8, (u32x4){lo.x, lo.y, hi.x, hi.y}), pf, O[dt], 0, 0, 0); }
;         }
;         lsum += __shfl_xor(lsum, 16); lsum += __shfl_xor(lsum, 32);
;         const float inv = __builtin_amdgcn_rcpf(lsum + __builtin_amdgcn_exp2f(sinkl - mx));
;         bf16_t* op = (bf16_t*)(a.ws + WS_B) + (zrow0 + t) * 512 + h * 64 + 4 * qd;
; #pragma unroll
;         for (int dt = 0; dt < 4; ++dt) { u32x2 w; w.x = pk2(O[dt][0] * inv, O[dt][1] * inv); w.y = pk2(O[dt][2] * inv, O[dt][3] * inv); *(u32x2*)(op + dt * 16) = w; }
	v_mfma_f32_16x16x32_bf16 v[38:41], v[50:53], v[46:49], v[38:41]
	v_cvt_pk_bf16_f32 v50, v81, v83
	v_cvt_pk_bf16_f32 v51, v65, v67
	v_cvt_pk_bf16_f32 v52, v69, v70
	s_waitcnt lgkmcnt(0)
	v_mfma_f32_16x16x32_bf16 v[30:33], v[42:45], v[46:49], v[30:33]
	v_cndmask_b32_e32 v72, 0, v54, vcc
	v_cmp_lt_f32_e32 vcc, s92, v59
	v_cvt_pk_bf16_f32 v53, v71, v72
	ds_read2_b64 v[54:57], v63 offset0:88 offset1:92
	ds_read2_b64 v[42:45], v82 offset0:24 offset1:28
	v_cndmask_b32_e32 v59, 0, v20, vcc
	v_sub_f32_e32 v20, v64, v66
	v_exp_f32_e32 v20, v20
	ds_read2_b64 v[46:49], v84 offset0:216 offset1:220
	v_cmp_lt_f32_e32 vcc, s92, v64
	s_waitcnt lgkmcnt(2)
	v_mfma_f32_16x16x32_bf16 v[34:37], v[54:57], v[50:53], v[34:37]
	v_cndmask_b32_e32 v64, 0, v20, vcc
	v_sub_f32_e32 v20, v62, v66
	v_exp_f32_e32 v26, v20
	v_sub_f32_e32 v20, v58, v66
	v_exp_f32_e32 v27, v20
	v_cmp_lt_f32_e32 vcc, s92, v62
	s_waitcnt lgkmcnt(1)
	v_mfma_f32_16x16x32_bf16 v[20:23], v[42:45], v[50:53], v[22:25]
	v_add_f32_e32 v56, v69, v68
	v_cndmask_b32_e32 v54, 0, v26, vcc
	v_cmp_lt_f32_e32 vcc, s92, v58
	v_add_f32_e32 v56, v70, v56
	v_add_f32_e32 v56, v71, v56
	v_cndmask_b32_e32 v55, 0, v27, vcc
	s_waitcnt lgkmcnt(0)
	v_mfma_f32_16x16x32_bf16 v[24:27], v[46:49], v[50:53], v[38:41]
	v_exp_f32_e32 v0, v0
	s_nop 1
	ds_read2_b64 v[38:41], v85 offset0:152 offset1:156
	v_cvt_pk_bf16_f32 v42, v59, v64
	v_cvt_pk_bf16_f32 v43, v54, v55
	v_cvt_pk_bf16_f32 v44, v1, v1
	v_cvt_pk_bf16_f32 v45, v1, v1
	ds_read2_b64 v[46:49], v63 offset0:96 offset1:100
	s_waitcnt lgkmcnt(1)
	v_mfma_f32_16x16x32_bf16 v[30:33], v[38:41], v[50:53], v[30:33]
	ds_read2_b64 v[38:41], v82 offset0:32 offset1:36
	v_add_f32_e32 v50, v72, v56
	v_add_f32_e32 v50, v59, v50
	v_add_f32_e32 v50, v64, v50
	s_waitcnt lgkmcnt(1)
	v_mfma_f32_16x16x32_bf16 v[34:37], v[46:49], v[42:45], v[34:37]
	ds_read2_b64 v[46:49], v84 offset0:224 offset1:228
	v_add_f32_e32 v50, v54, v50
	v_add_f32_e32 v50, v55, v50
	v_add_f32_e32 v50, 0, v50
	ds_bpermute_b32 v28, v28, v50
	s_waitcnt lgkmcnt(2)
	v_mfma_f32_16x16x32_bf16 v[20:23], v[38:41], v[42:45], v[20:23]
	ds_read2_b64 v[38:41], v85 offset0:160 offset1:164
	s_waitcnt lgkmcnt(2)
	v_mfma_f32_16x16x32_bf16 v[24:27], v[46:49], v[42:45], v[24:27]
	s_waitcnt lgkmcnt(1)
	v_add_f32_e32 v46, v50, v28
	ds_bpermute_b32 v47, v29, v46
	s_waitcnt lgkmcnt(1)
	v_mfma_f32_16x16x32_bf16 v[28:31], v[38:41], v[42:45], v[30:33]
	s_waitcnt lgkmcnt(0)
	s_nop 1
	v_add_f32_e32 v32, v46, v47
	v_add_f32_e32 v0, v0, v32
	v_rcp_f32_e32 v38, v0
	v_lshlrev_b32_e32 v0, 1, v61
	v_lshl_add_u64 v[2:3], v[2:3], 0, v[0:1]
	v_mov_b32_e32 v61, v1
	v_mul_f32_e32 v0, v34, v38
	v_mul_f32_e32 v32, v35, v38
	v_cvt_pk_bf16_f32 v32, v0, v32
	v_mul_f32_e32 v0, v36, v38
	v_mul_f32_e32 v33, v37, v38
	v_lshl_add_u64 v[2:3], v[2:3], 0, v[60:61]
	v_cvt_pk_bf16_f32 v33, v0, v33
	v_mul_f32_e32 v0, v20, v38
	v_mul_f32_e32 v20, v21, v38
	v_mul_f32_e32 v21, v23, v38
	global_store_dwordx2 v[2:3], v[32:33], off
	v_cvt_pk_bf16_f32 v20, v0, v20
	v_mul_f32_e32 v0, v22, v38
	v_cvt_pk_bf16_f32 v21, v0, v21
	global_store_dwordx2 v[2:3], v[20:21], off offset:32
	v_mul_f32_e32 v0, v24, v38
	v_mul_f32_e32 v20, v25, v38
	v_mul_f32_e32 v21, v27, v38
	v_cvt_pk_bf16_f32 v20, v0, v20
	v_mul_f32_e32 v0, v26, v38
	v_cvt_pk_bf16_f32 v21, v0, v21
	global_store_dwordx2 v[2:3], v[20:21], off offset:64
	v_mul_f32_e32 v0, v28, v38
	v_mul_f32_e32 v20, v29, v38
	v_mul_f32_e32 v21, v31, v38
	v_cvt_pk_bf16_f32 v20, v0, v20
	v_mul_f32_e32 v0, v30, v38
	v_cvt_pk_bf16_f32 v21, v0, v21
	global_store_dwordx2 v[2:3], v[20:21], off offset:96
	s_branch .LBB0_595
